# v15: v13 + P6b walks each wave's rows from the highest to the lowest (consume the act rows P6 wrote last first: they are the ones still in the memory-side cache)
# baseline (speedup 1.0000x reference)
.LBB0_906:
	s_or_b64 exec, exec, s[6:7]
	s_mov_b32 s2, 0
	s_waitcnt lgkmcnt(0)
	s_barrier
	s_mov_b64 s[6:7], s[0:1]
	v_mbcnt_lo_u32_b32 v0, -1, s2
	v_mbcnt_hi_u32_b32 v2, -1, v0
	s_and_b64 vcc, exec, s[4:5]
	s_cbranch_vccnz .LBB0_911
	s_mov_b32 s86, s42
.Lp6b_rev:
	s_add_i32 s88, s86, s44
	s_cmpk_gt_i32 s88, 0x5fff
	s_cbranch_scc1 .Lp6b_rev_done
	s_mov_b32 s86, s88
	s_branch .Lp6b_rev
.Lp6b_rev_done:
	s_ashr_i32 s87, s86, 31
	s_sub_i32 s88, 0, s44
	s_ashr_i32 s89, s88, 31
	v_lshlrev_b32_e32 v0, 30, v2
	s_load_dwordx2 s[8:9], s[6:7], 0x88
	v_and_b32_e32 v83, 0x80000000, v0
	v_lshlrev_b32_e32 v0, 29, v2
	v_ashrrev_i32_e32 v3, 31, v2
	v_and_b32_e32 v84, 0x80000000, v0
	s_lshl_b64 s[2:3], s[86:87], 2
	v_lshlrev_b64 v[0:1], 2, v[2:3]
	v_mov_b32_e32 v4, 0x2b00
	v_lshlrev_b32_e32 v82, 31, v2
	v_cmp_eq_u32_e64 s[6:7], 0, v2
	s_add_u32 s2, s2, 0x80000
	v_mad_i64_i32 v[0:1], s[12:13], s86, v4, v[0:1]
	v_lshlrev_b64 v[2:3], 3, v[2:3]
	v_mov_b32_e32 v4, 0x5600
	s_addc_u32 s3, s3, 0
	s_ashr_i32 s45, s44, 31
	v_mad_i64_i32 v[2:3], s[16:17], s86, v4, v[2:3]
	s_lshl_b64 s[10:11], s[88:89], 2
	s_mul_hi_i32 s13, s88, 0x2b00
	s_mul_i32 s12, s88, 0x2b00
	s_mul_hi_i32 s17, s88, 0x5600
	s_mul_i32 s16, s88, 0x5600
	s_mov_b32 s22, 0x23001000
	s_mov_b32 s23, 0x23002000
	s_mov_b32 s24, 0x23003000
	s_mov_b32 s25, 0x23004000
	s_mov_b32 s26, 0x23005000
	v_mov_b32_e32 v85, 0
	s_mov_b32 s27, 0x42fe0000
	s_mov_b32 s28, 0xc0c0400
	s_mov_b32 s29, 0x5040100
	s_mov_b32 s30, 0x400000
	s_mov_b32 s31, 0x401000
	s_mov_b32 s34, 0x402000
	s_mov_b32 s35, s86
	s_branch .LBB0_909
.LBB0_908:
	s_or_b64 exec, exec, s[18:19]
	s_add_i32 s35, s35, s88
	s_add_u32 s2, s2, s10
	s_addc_u32 s3, s3, s11
	v_lshl_add_u64 v[0:1], v[0:1], 0, s[12:13]
	s_cmpk_lt_i32 s35, 0
	v_lshl_add_u64 v[2:3], v[2:3], 0, s[16:17]
	s_cbranch_scc1 .LBB0_911
